# SwiGLU epilogue (packed) + sc1 write-through stores of the activation tile
# baseline (speedup 1.0000x reference)
.LBB0_259:
	v_mov_b32_e32 v74, s88
	v_mov_b32_e32 v75, s89
	ds_read_b32 v74, v74
	ds_read_b32 v75, v75
	ds_read2_b32 v[76:77], v173 offset1:16
	ds_read2_b32 v[78:79], v173 offset0:32 offset1:48
	ds_read2_b32 v[80:81], v173 offset0:64 offset1:80
	ds_read2_b32 v[90:91], v173 offset0:96 offset1:112
	ds_read_b128 v[188:191], v179 offset:512
	ds_read_b128 v[192:195], v179 offset:528
	ds_read_b128 v[196:199], v179 offset:544
	ds_read_b128 v[200:203], v179 offset:560
	v_lshl_or_b32 v186, s3, 7, v175
	v_ashrrev_i32_e32 v187, 31, v186
	v_lshl_add_u32 v155, s46, 8, v1
	v_mov_b32_e32 v204, 0xbfb8aa3b
	v_mov_b32_e32 v205, 1.0
	s_waitcnt lgkmcnt(8)
	v_lshl_add_u64 v[168:169], v[186:187], 1, v[74:75]
	v_lshl_add_u64 v[168:169], v[168:169], 0, s[78:79]
	v_mad_i64_i32 v[214:215], s[20:21], v155, s71, v[168:169]
	s_waitcnt lgkmcnt(4)
	v_fmamk_f32 v184, v76, 0x3a800000, v229
	v_fmamk_f32 v182, v77, 0x3a800000, v229
	v_fmamk_f32 v180, v78, 0x3a800000, v229
	v_fmamk_f32 v178, v79, 0x3a800000, v229
	v_fmamk_f32 v176, v80, 0x3a800000, v229
	v_fmamk_f32 v174, v81, 0x3a800000, v229
	v_fmamk_f32 v172, v90, 0x3a800000, v229
	v_fmamk_f32 v170, v91, 0x3a800000, v229
	v_rsq_f32_e32 v184, v184
	v_rsq_f32_e32 v182, v182
	v_rsq_f32_e32 v180, v180
	v_rsq_f32_e32 v178, v178
	v_rsq_f32_e32 v176, v176
	v_rsq_f32_e32 v174, v174
	v_rsq_f32_e32 v172, v172
	v_rsq_f32_e32 v170, v170
	s_mov_b32 s20, 0x16000
	s_mov_b32 s21, 0
	s_waitcnt lgkmcnt(0)
	v_pk_fma_f32 v[142:143], v[142:143], v[184:185], v[188:189] op_sel_hi:[1,0,1]
	v_pk_fma_f32 v[144:145], v[144:145], v[184:185], v[190:191] op_sel_hi:[1,0,1]
	v_pk_fma_f32 v[134:135], v[134:135], v[184:185], v[192:193] op_sel_hi:[1,0,1]
	v_pk_fma_f32 v[136:137], v[136:137], v[184:185], v[194:195] op_sel_hi:[1,0,1]
	v_pk_mul_f32 v[206:207], v[142:143], v[204:205] op_sel_hi:[1,0]
	v_pk_mul_f32 v[208:209], v[144:145], v[204:205] op_sel_hi:[1,0]
	v_pk_mul_f32 v[210:211], v[134:135], v[204:205] op_sel_hi:[1,0]
	v_pk_mul_f32 v[212:213], v[136:137], v[204:205] op_sel_hi:[1,0]
	v_pk_fma_f32 v[138:139], v[138:139], v[184:185], v[196:197] op_sel_hi:[1,0,1]
	v_pk_fma_f32 v[140:141], v[140:141], v[184:185], v[198:199] op_sel_hi:[1,0,1]
	v_pk_fma_f32 v[130:131], v[130:131], v[184:185], v[200:201] op_sel_hi:[1,0,1]
	v_pk_fma_f32 v[132:133], v[132:133], v[184:185], v[202:203] op_sel_hi:[1,0,1]
	v_exp_f32_e32 v206, v206
	v_exp_f32_e32 v207, v207
	v_exp_f32_e32 v208, v208
	v_exp_f32_e32 v209, v209
	v_exp_f32_e32 v210, v210
	v_exp_f32_e32 v211, v211
	v_exp_f32_e32 v212, v212
	v_exp_f32_e32 v213, v213
	v_pk_add_f32 v[206:207], v[206:207], v[204:205] op_sel:[0,1] op_sel_hi:[1,1]
	v_pk_add_f32 v[208:209], v[208:209], v[204:205] op_sel:[0,1] op_sel_hi:[1,1]
	v_pk_add_f32 v[210:211], v[210:211], v[204:205] op_sel:[0,1] op_sel_hi:[1,1]
	v_pk_add_f32 v[212:213], v[212:213], v[204:205] op_sel:[0,1] op_sel_hi:[1,1]
	v_rcp_f32_e32 v206, v206
	v_rcp_f32_e32 v207, v207
	v_rcp_f32_e32 v208, v208
	v_rcp_f32_e32 v209, v209
	v_rcp_f32_e32 v210, v210
	v_rcp_f32_e32 v211, v211
	v_rcp_f32_e32 v212, v212
	v_rcp_f32_e32 v213, v213
	v_pk_mul_f32 v[142:143], v[142:143], v[206:207]
	v_pk_mul_f32 v[144:145], v[144:145], v[208:209]
	v_pk_mul_f32 v[134:135], v[134:135], v[210:211]
	v_pk_mul_f32 v[136:137], v[136:137], v[212:213]
	v_pk_mul_f32 v[138:139], v[138:139], v[142:143]
	v_pk_mul_f32 v[140:141], v[140:141], v[144:145]
	v_pk_mul_f32 v[130:131], v[130:131], v[134:135]
	v_pk_mul_f32 v[132:133], v[132:133], v[136:137]
	v_cvt_pk_bf16_f32 v142, v138, v139
	v_cvt_pk_bf16_f32 v143, v140, v141
	v_cvt_pk_bf16_f32 v144, v130, v131
	v_cvt_pk_bf16_f32 v145, v132, v133
	global_store_dwordx4 v[214:215], v[142:145], off sc1
	v_lshl_add_u64 v[216:217], v[214:215], 0, s[20:21]
	v_pk_fma_f32 v[126:127], v[126:127], v[182:183], v[188:189] op_sel_hi:[1,0,1]
	v_pk_fma_f32 v[128:129], v[128:129], v[182:183], v[190:191] op_sel_hi:[1,0,1]
	v_pk_fma_f32 v[118:119], v[118:119], v[182:183], v[192:193] op_sel_hi:[1,0,1]
	v_pk_fma_f32 v[120:121], v[120:121], v[182:183], v[194:195] op_sel_hi:[1,0,1]
	v_pk_mul_f32 v[206:207], v[126:127], v[204:205] op_sel_hi:[1,0]
	v_pk_mul_f32 v[208:209], v[128:129], v[204:205] op_sel_hi:[1,0]
	v_pk_mul_f32 v[210:211], v[118:119], v[204:205] op_sel_hi:[1,0]
	v_pk_mul_f32 v[212:213], v[120:121], v[204:205] op_sel_hi:[1,0]
	v_pk_fma_f32 v[122:123], v[122:123], v[182:183], v[196:197] op_sel_hi:[1,0,1]
	v_pk_fma_f32 v[124:125], v[124:125], v[182:183], v[198:199] op_sel_hi:[1,0,1]
	v_pk_fma_f32 v[114:115], v[114:115], v[182:183], v[200:201] op_sel_hi:[1,0,1]
	v_pk_fma_f32 v[116:117], v[116:117], v[182:183], v[202:203] op_sel_hi:[1,0,1]
	v_exp_f32_e32 v206, v206
	v_exp_f32_e32 v207, v207
	v_exp_f32_e32 v208, v208
	v_exp_f32_e32 v209, v209
	v_exp_f32_e32 v210, v210
	v_exp_f32_e32 v211, v211
	v_exp_f32_e32 v212, v212
	v_exp_f32_e32 v213, v213
	v_pk_add_f32 v[206:207], v[206:207], v[204:205] op_sel:[0,1] op_sel_hi:[1,1]
	v_pk_add_f32 v[208:209], v[208:209], v[204:205] op_sel:[0,1] op_sel_hi:[1,1]
	v_pk_add_f32 v[210:211], v[210:211], v[204:205] op_sel:[0,1] op_sel_hi:[1,1]
	v_pk_add_f32 v[212:213], v[212:213], v[204:205] op_sel:[0,1] op_sel_hi:[1,1]
	v_rcp_f32_e32 v206, v206
	v_rcp_f32_e32 v207, v207
	v_rcp_f32_e32 v208, v208
	v_rcp_f32_e32 v209, v209
	v_rcp_f32_e32 v210, v210
	v_rcp_f32_e32 v211, v211
	v_rcp_f32_e32 v212, v212
	v_rcp_f32_e32 v213, v213
	v_pk_mul_f32 v[126:127], v[126:127], v[206:207]
	v_pk_mul_f32 v[128:129], v[128:129], v[208:209]
	v_pk_mul_f32 v[118:119], v[118:119], v[210:211]
	v_pk_mul_f32 v[120:121], v[120:121], v[212:213]
	v_pk_mul_f32 v[122:123], v[122:123], v[126:127]
	v_pk_mul_f32 v[124:125], v[124:125], v[128:129]
	v_pk_mul_f32 v[114:115], v[114:115], v[118:119]
	v_pk_mul_f32 v[116:117], v[116:117], v[120:121]
	v_cvt_pk_bf16_f32 v126, v122, v123
	v_cvt_pk_bf16_f32 v127, v124, v125
	v_cvt_pk_bf16_f32 v128, v114, v115
	v_cvt_pk_bf16_f32 v129, v116, v117
	global_store_dwordx4 v[216:217], v[126:129], off sc1
	v_lshl_add_u64 v[214:215], v[216:217], 0, s[20:21]
	v_pk_fma_f32 v[110:111], v[110:111], v[180:181], v[188:189] op_sel_hi:[1,0,1]
	v_pk_fma_f32 v[112:113], v[112:113], v[180:181], v[190:191] op_sel_hi:[1,0,1]
	v_pk_fma_f32 v[102:103], v[102:103], v[180:181], v[192:193] op_sel_hi:[1,0,1]
	v_pk_fma_f32 v[104:105], v[104:105], v[180:181], v[194:195] op_sel_hi:[1,0,1]
	v_pk_mul_f32 v[206:207], v[110:111], v[204:205] op_sel_hi:[1,0]
	v_pk_mul_f32 v[208:209], v[112:113], v[204:205] op_sel_hi:[1,0]
	v_pk_mul_f32 v[210:211], v[102:103], v[204:205] op_sel_hi:[1,0]
	v_pk_mul_f32 v[212:213], v[104:105], v[204:205] op_sel_hi:[1,0]
	v_pk_fma_f32 v[106:107], v[106:107], v[180:181], v[196:197] op_sel_hi:[1,0,1]
	v_pk_fma_f32 v[108:109], v[108:109], v[180:181], v[198:199] op_sel_hi:[1,0,1]
	v_pk_fma_f32 v[98:99], v[98:99], v[180:181], v[200:201] op_sel_hi:[1,0,1]
	v_pk_fma_f32 v[100:101], v[100:101], v[180:181], v[202:203] op_sel_hi:[1,0,1]
	v_exp_f32_e32 v206, v206
	v_exp_f32_e32 v207, v207
	v_exp_f32_e32 v208, v208
	v_exp_f32_e32 v209, v209
	v_exp_f32_e32 v210, v210
	v_exp_f32_e32 v211, v211
	v_exp_f32_e32 v212, v212
	v_exp_f32_e32 v213, v213
	v_pk_add_f32 v[206:207], v[206:207], v[204:205] op_sel:[0,1] op_sel_hi:[1,1]
	v_pk_add_f32 v[208:209], v[208:209], v[204:205] op_sel:[0,1] op_sel_hi:[1,1]
	v_pk_add_f32 v[210:211], v[210:211], v[204:205] op_sel:[0,1] op_sel_hi:[1,1]
	v_pk_add_f32 v[212:213], v[212:213], v[204:205] op_sel:[0,1] op_sel_hi:[1,1]
	v_rcp_f32_e32 v206, v206
	v_rcp_f32_e32 v207, v207
	v_rcp_f32_e32 v208, v208
	v_rcp_f32_e32 v209, v209
	v_rcp_f32_e32 v210, v210
	v_rcp_f32_e32 v211, v211
	v_rcp_f32_e32 v212, v212
	v_rcp_f32_e32 v213, v213
	v_pk_mul_f32 v[110:111], v[110:111], v[206:207]
	v_pk_mul_f32 v[112:113], v[112:113], v[208:209]
	v_pk_mul_f32 v[102:103], v[102:103], v[210:211]
	v_pk_mul_f32 v[104:105], v[104:105], v[212:213]
	v_pk_mul_f32 v[106:107], v[106:107], v[110:111]
	v_pk_mul_f32 v[108:109], v[108:109], v[112:113]
	v_pk_mul_f32 v[98:99], v[98:99], v[102:103]
	v_pk_mul_f32 v[100:101], v[100:101], v[104:105]
	v_cvt_pk_bf16_f32 v110, v106, v107
	v_cvt_pk_bf16_f32 v111, v108, v109
	v_cvt_pk_bf16_f32 v112, v98, v99
	v_cvt_pk_bf16_f32 v113, v100, v101
	global_store_dwordx4 v[214:215], v[110:113], off sc1
	v_lshl_add_u64 v[216:217], v[214:215], 0, s[20:21]
	v_pk_fma_f32 v[86:87], v[86:87], v[178:179], v[188:189] op_sel_hi:[1,0,1]
	v_pk_fma_f32 v[88:89], v[88:89], v[178:179], v[190:191] op_sel_hi:[1,0,1]
	v_pk_fma_f32 v[70:71], v[70:71], v[178:179], v[192:193] op_sel_hi:[1,0,1]
	v_pk_fma_f32 v[72:73], v[72:73], v[178:179], v[194:195] op_sel_hi:[1,0,1]
	v_pk_mul_f32 v[206:207], v[86:87], v[204:205] op_sel_hi:[1,0]
	v_pk_mul_f32 v[208:209], v[88:89], v[204:205] op_sel_hi:[1,0]
	v_pk_mul_f32 v[210:211], v[70:71], v[204:205] op_sel_hi:[1,0]
	v_pk_mul_f32 v[212:213], v[72:73], v[204:205] op_sel_hi:[1,0]
	v_pk_fma_f32 v[82:83], v[82:83], v[178:179], v[196:197] op_sel_hi:[1,0,1]
	v_pk_fma_f32 v[84:85], v[84:85], v[178:179], v[198:199] op_sel_hi:[1,0,1]
	v_pk_fma_f32 v[66:67], v[66:67], v[178:179], v[200:201] op_sel_hi:[1,0,1]
	v_pk_fma_f32 v[68:69], v[68:69], v[178:179], v[202:203] op_sel_hi:[1,0,1]
	v_exp_f32_e32 v206, v206
	v_exp_f32_e32 v207, v207
	v_exp_f32_e32 v208, v208
	v_exp_f32_e32 v209, v209
	v_exp_f32_e32 v210, v210
	v_exp_f32_e32 v211, v211
	v_exp_f32_e32 v212, v212
	v_exp_f32_e32 v213, v213
	v_pk_add_f32 v[206:207], v[206:207], v[204:205] op_sel:[0,1] op_sel_hi:[1,1]
	v_pk_add_f32 v[208:209], v[208:209], v[204:205] op_sel:[0,1] op_sel_hi:[1,1]
	v_pk_add_f32 v[210:211], v[210:211], v[204:205] op_sel:[0,1] op_sel_hi:[1,1]
	v_pk_add_f32 v[212:213], v[212:213], v[204:205] op_sel:[0,1] op_sel_hi:[1,1]
	v_rcp_f32_e32 v206, v206
	v_rcp_f32_e32 v207, v207
	v_rcp_f32_e32 v208, v208
	v_rcp_f32_e32 v209, v209
	v_rcp_f32_e32 v210, v210
	v_rcp_f32_e32 v211, v211
	v_rcp_f32_e32 v212, v212
	v_rcp_f32_e32 v213, v213
	v_pk_mul_f32 v[86:87], v[86:87], v[206:207]
	v_pk_mul_f32 v[88:89], v[88:89], v[208:209]
	v_pk_mul_f32 v[70:71], v[70:71], v[210:211]
	v_pk_mul_f32 v[72:73], v[72:73], v[212:213]
	v_pk_mul_f32 v[82:83], v[82:83], v[86:87]
	v_pk_mul_f32 v[84:85], v[84:85], v[88:89]
	v_pk_mul_f32 v[66:67], v[66:67], v[70:71]
	v_pk_mul_f32 v[68:69], v[68:69], v[72:73]
	v_cvt_pk_bf16_f32 v86, v82, v83
	v_cvt_pk_bf16_f32 v87, v84, v85
	v_cvt_pk_bf16_f32 v88, v66, v67
	v_cvt_pk_bf16_f32 v89, v68, v69
	global_store_dwordx4 v[216:217], v[86:89], off sc1
	s_mov_b32 s20, 0x6e000
	v_lshl_add_u64 v[214:215], v[216:217], 0, s[20:21]
	s_mov_b32 s20, 0x16000
	v_pk_fma_f32 v[62:63], v[62:63], v[176:177], v[188:189] op_sel_hi:[1,0,1]
	v_pk_fma_f32 v[64:65], v[64:65], v[176:177], v[190:191] op_sel_hi:[1,0,1]
	v_pk_fma_f32 v[54:55], v[54:55], v[176:177], v[192:193] op_sel_hi:[1,0,1]
	v_pk_fma_f32 v[56:57], v[56:57], v[176:177], v[194:195] op_sel_hi:[1,0,1]
	v_pk_mul_f32 v[206:207], v[62:63], v[204:205] op_sel_hi:[1,0]
	v_pk_mul_f32 v[208:209], v[64:65], v[204:205] op_sel_hi:[1,0]
	v_pk_mul_f32 v[210:211], v[54:55], v[204:205] op_sel_hi:[1,0]
	v_pk_mul_f32 v[212:213], v[56:57], v[204:205] op_sel_hi:[1,0]
	v_pk_fma_f32 v[58:59], v[58:59], v[176:177], v[196:197] op_sel_hi:[1,0,1]
	v_pk_fma_f32 v[60:61], v[60:61], v[176:177], v[198:199] op_sel_hi:[1,0,1]
	v_pk_fma_f32 v[50:51], v[50:51], v[176:177], v[200:201] op_sel_hi:[1,0,1]
	v_pk_fma_f32 v[52:53], v[52:53], v[176:177], v[202:203] op_sel_hi:[1,0,1]
	v_exp_f32_e32 v206, v206
	v_exp_f32_e32 v207, v207
	v_exp_f32_e32 v208, v208
	v_exp_f32_e32 v209, v209
	v_exp_f32_e32 v210, v210
	v_exp_f32_e32 v211, v211
	v_exp_f32_e32 v212, v212
	v_exp_f32_e32 v213, v213
	v_pk_add_f32 v[206:207], v[206:207], v[204:205] op_sel:[0,1] op_sel_hi:[1,1]
	v_pk_add_f32 v[208:209], v[208:209], v[204:205] op_sel:[0,1] op_sel_hi:[1,1]
	v_pk_add_f32 v[210:211], v[210:211], v[204:205] op_sel:[0,1] op_sel_hi:[1,1]
	v_pk_add_f32 v[212:213], v[212:213], v[204:205] op_sel:[0,1] op_sel_hi:[1,1]
	v_rcp_f32_e32 v206, v206
	v_rcp_f32_e32 v207, v207
	v_rcp_f32_e32 v208, v208
	v_rcp_f32_e32 v209, v209
	v_rcp_f32_e32 v210, v210
	v_rcp_f32_e32 v211, v211
	v_rcp_f32_e32 v212, v212
	v_rcp_f32_e32 v213, v213
	v_pk_mul_f32 v[62:63], v[62:63], v[206:207]
	v_pk_mul_f32 v[64:65], v[64:65], v[208:209]
	v_pk_mul_f32 v[54:55], v[54:55], v[210:211]
	v_pk_mul_f32 v[56:57], v[56:57], v[212:213]
	v_pk_mul_f32 v[58:59], v[58:59], v[62:63]
	v_pk_mul_f32 v[60:61], v[60:61], v[64:65]
	v_pk_mul_f32 v[50:51], v[50:51], v[54:55]
	v_pk_mul_f32 v[52:53], v[52:53], v[56:57]
	v_cvt_pk_bf16_f32 v62, v58, v59
	v_cvt_pk_bf16_f32 v63, v60, v61
	v_cvt_pk_bf16_f32 v64, v50, v51
	v_cvt_pk_bf16_f32 v65, v52, v53
	global_store_dwordx4 v[214:215], v[62:65], off sc1
	v_lshl_add_u64 v[216:217], v[214:215], 0, s[20:21]
	v_pk_fma_f32 v[46:47], v[46:47], v[174:175], v[188:189] op_sel_hi:[1,0,1]
	v_pk_fma_f32 v[48:49], v[48:49], v[174:175], v[190:191] op_sel_hi:[1,0,1]
	v_pk_fma_f32 v[38:39], v[38:39], v[174:175], v[192:193] op_sel_hi:[1,0,1]
	v_pk_fma_f32 v[40:41], v[40:41], v[174:175], v[194:195] op_sel_hi:[1,0,1]
	v_pk_mul_f32 v[206:207], v[46:47], v[204:205] op_sel_hi:[1,0]
	v_pk_mul_f32 v[208:209], v[48:49], v[204:205] op_sel_hi:[1,0]
	v_pk_mul_f32 v[210:211], v[38:39], v[204:205] op_sel_hi:[1,0]
	v_pk_mul_f32 v[212:213], v[40:41], v[204:205] op_sel_hi:[1,0]
	v_pk_fma_f32 v[42:43], v[42:43], v[174:175], v[196:197] op_sel_hi:[1,0,1]
	v_pk_fma_f32 v[44:45], v[44:45], v[174:175], v[198:199] op_sel_hi:[1,0,1]
	v_pk_fma_f32 v[34:35], v[34:35], v[174:175], v[200:201] op_sel_hi:[1,0,1]
	v_pk_fma_f32 v[36:37], v[36:37], v[174:175], v[202:203] op_sel_hi:[1,0,1]
	v_exp_f32_e32 v206, v206
	v_exp_f32_e32 v207, v207
	v_exp_f32_e32 v208, v208
	v_exp_f32_e32 v209, v209
	v_exp_f32_e32 v210, v210
	v_exp_f32_e32 v211, v211
	v_exp_f32_e32 v212, v212
	v_exp_f32_e32 v213, v213
	v_pk_add_f32 v[206:207], v[206:207], v[204:205] op_sel:[0,1] op_sel_hi:[1,1]
	v_pk_add_f32 v[208:209], v[208:209], v[204:205] op_sel:[0,1] op_sel_hi:[1,1]
	v_pk_add_f32 v[210:211], v[210:211], v[204:205] op_sel:[0,1] op_sel_hi:[1,1]
	v_pk_add_f32 v[212:213], v[212:213], v[204:205] op_sel:[0,1] op_sel_hi:[1,1]
	v_rcp_f32_e32 v206, v206
	v_rcp_f32_e32 v207, v207
	v_rcp_f32_e32 v208, v208
	v_rcp_f32_e32 v209, v209
	v_rcp_f32_e32 v210, v210
	v_rcp_f32_e32 v211, v211
	v_rcp_f32_e32 v212, v212
	v_rcp_f32_e32 v213, v213
	v_pk_mul_f32 v[46:47], v[46:47], v[206:207]
	v_pk_mul_f32 v[48:49], v[48:49], v[208:209]
	v_pk_mul_f32 v[38:39], v[38:39], v[210:211]
	v_pk_mul_f32 v[40:41], v[40:41], v[212:213]
	v_pk_mul_f32 v[42:43], v[42:43], v[46:47]
	v_pk_mul_f32 v[44:45], v[44:45], v[48:49]
	v_pk_mul_f32 v[34:35], v[34:35], v[38:39]
	v_pk_mul_f32 v[36:37], v[36:37], v[40:41]
	v_cvt_pk_bf16_f32 v46, v42, v43
	v_cvt_pk_bf16_f32 v47, v44, v45
	v_cvt_pk_bf16_f32 v48, v34, v35
	v_cvt_pk_bf16_f32 v49, v36, v37
	global_store_dwordx4 v[216:217], v[46:49], off sc1
	v_lshl_add_u64 v[214:215], v[216:217], 0, s[20:21]
	v_pk_fma_f32 v[30:31], v[30:31], v[172:173], v[188:189] op_sel_hi:[1,0,1]
	v_pk_fma_f32 v[32:33], v[32:33], v[172:173], v[190:191] op_sel_hi:[1,0,1]
	v_pk_fma_f32 v[22:23], v[22:23], v[172:173], v[192:193] op_sel_hi:[1,0,1]
	v_pk_fma_f32 v[24:25], v[24:25], v[172:173], v[194:195] op_sel_hi:[1,0,1]
	v_pk_mul_f32 v[206:207], v[30:31], v[204:205] op_sel_hi:[1,0]
	v_pk_mul_f32 v[208:209], v[32:33], v[204:205] op_sel_hi:[1,0]
	v_pk_mul_f32 v[210:211], v[22:23], v[204:205] op_sel_hi:[1,0]
	v_pk_mul_f32 v[212:213], v[24:25], v[204:205] op_sel_hi:[1,0]
	v_pk_fma_f32 v[26:27], v[26:27], v[172:173], v[196:197] op_sel_hi:[1,0,1]
	v_pk_fma_f32 v[28:29], v[28:29], v[172:173], v[198:199] op_sel_hi:[1,0,1]
	v_pk_fma_f32 v[18:19], v[18:19], v[172:173], v[200:201] op_sel_hi:[1,0,1]
	v_pk_fma_f32 v[20:21], v[20:21], v[172:173], v[202:203] op_sel_hi:[1,0,1]
	v_exp_f32_e32 v206, v206
	v_exp_f32_e32 v207, v207
	v_exp_f32_e32 v208, v208
	v_exp_f32_e32 v209, v209
	v_exp_f32_e32 v210, v210
	v_exp_f32_e32 v211, v211
	v_exp_f32_e32 v212, v212
	v_exp_f32_e32 v213, v213
	v_pk_add_f32 v[206:207], v[206:207], v[204:205] op_sel:[0,1] op_sel_hi:[1,1]
	v_pk_add_f32 v[208:209], v[208:209], v[204:205] op_sel:[0,1] op_sel_hi:[1,1]
	v_pk_add_f32 v[210:211], v[210:211], v[204:205] op_sel:[0,1] op_sel_hi:[1,1]
	v_pk_add_f32 v[212:213], v[212:213], v[204:205] op_sel:[0,1] op_sel_hi:[1,1]
	v_rcp_f32_e32 v206, v206
	v_rcp_f32_e32 v207, v207
	v_rcp_f32_e32 v208, v208
	v_rcp_f32_e32 v209, v209
	v_rcp_f32_e32 v210, v210
	v_rcp_f32_e32 v211, v211
	v_rcp_f32_e32 v212, v212
	v_rcp_f32_e32 v213, v213
	v_pk_mul_f32 v[30:31], v[30:31], v[206:207]
	v_pk_mul_f32 v[32:33], v[32:33], v[208:209]
	v_pk_mul_f32 v[22:23], v[22:23], v[210:211]
	v_pk_mul_f32 v[24:25], v[24:25], v[212:213]
	v_pk_mul_f32 v[26:27], v[26:27], v[30:31]
	v_pk_mul_f32 v[28:29], v[28:29], v[32:33]
	v_pk_mul_f32 v[18:19], v[18:19], v[22:23]
	v_pk_mul_f32 v[20:21], v[20:21], v[24:25]
	v_cvt_pk_bf16_f32 v30, v26, v27
	v_cvt_pk_bf16_f32 v31, v28, v29
	v_cvt_pk_bf16_f32 v32, v18, v19
	v_cvt_pk_bf16_f32 v33, v20, v21
	global_store_dwordx4 v[214:215], v[30:33], off sc1
	v_lshl_add_u64 v[216:217], v[214:215], 0, s[20:21]
	v_pk_fma_f32 v[14:15], v[14:15], v[170:171], v[188:189] op_sel_hi:[1,0,1]
	v_pk_fma_f32 v[16:17], v[16:17], v[170:171], v[190:191] op_sel_hi:[1,0,1]
	v_pk_fma_f32 v[6:7], v[6:7], v[170:171], v[192:193] op_sel_hi:[1,0,1]
	v_pk_fma_f32 v[8:9], v[8:9], v[170:171], v[194:195] op_sel_hi:[1,0,1]
	v_pk_mul_f32 v[206:207], v[14:15], v[204:205] op_sel_hi:[1,0]
	v_pk_mul_f32 v[208:209], v[16:17], v[204:205] op_sel_hi:[1,0]
	v_pk_mul_f32 v[210:211], v[6:7], v[204:205] op_sel_hi:[1,0]
	v_pk_mul_f32 v[212:213], v[8:9], v[204:205] op_sel_hi:[1,0]
	v_pk_fma_f32 v[10:11], v[10:11], v[170:171], v[196:197] op_sel_hi:[1,0,1]
	v_pk_fma_f32 v[12:13], v[12:13], v[170:171], v[198:199] op_sel_hi:[1,0,1]
	v_pk_fma_f32 v[2:3], v[2:3], v[170:171], v[200:201] op_sel_hi:[1,0,1]
	v_pk_fma_f32 v[4:5], v[4:5], v[170:171], v[202:203] op_sel_hi:[1,0,1]
	v_exp_f32_e32 v206, v206
	v_exp_f32_e32 v207, v207
	v_exp_f32_e32 v208, v208
	v_exp_f32_e32 v209, v209
	v_exp_f32_e32 v210, v210
	v_exp_f32_e32 v211, v211
	v_exp_f32_e32 v212, v212
	v_exp_f32_e32 v213, v213
	v_pk_add_f32 v[206:207], v[206:207], v[204:205] op_sel:[0,1] op_sel_hi:[1,1]
	v_pk_add_f32 v[208:209], v[208:209], v[204:205] op_sel:[0,1] op_sel_hi:[1,1]
	v_pk_add_f32 v[210:211], v[210:211], v[204:205] op_sel:[0,1] op_sel_hi:[1,1]
	v_pk_add_f32 v[212:213], v[212:213], v[204:205] op_sel:[0,1] op_sel_hi:[1,1]
	v_rcp_f32_e32 v206, v206
	v_rcp_f32_e32 v207, v207
	v_rcp_f32_e32 v208, v208
	v_rcp_f32_e32 v209, v209
	v_rcp_f32_e32 v210, v210
	v_rcp_f32_e32 v211, v211
	v_rcp_f32_e32 v212, v212
	v_rcp_f32_e32 v213, v213
	v_pk_mul_f32 v[14:15], v[14:15], v[206:207]
	v_pk_mul_f32 v[16:17], v[16:17], v[208:209]
	v_pk_mul_f32 v[6:7], v[6:7], v[210:211]
	v_pk_mul_f32 v[8:9], v[8:9], v[212:213]
	v_pk_mul_f32 v[10:11], v[10:11], v[14:15]
	v_pk_mul_f32 v[12:13], v[12:13], v[16:17]
	v_pk_mul_f32 v[2:3], v[2:3], v[6:7]
	v_pk_mul_f32 v[4:5], v[4:5], v[8:9]
	v_cvt_pk_bf16_f32 v14, v10, v11
	v_cvt_pk_bf16_f32 v15, v12, v13
	v_cvt_pk_bf16_f32 v16, v2, v3
	v_cvt_pk_bf16_f32 v17, v4, v5
	global_store_dwordx4 v[216:217], v[14:17], off sc1
	s_andn2_b64 vcc, exec, s[4:5]
	s_mov_b64 s[20:21], -1
	s_cbranch_vccnz .LBB0_252
	s_nop 0
	v_mov_b32_e32 v2, s88
	ds_read_b32 v2, v2
	v_mov_b32_e32 v3, s89
	ds_read_b32 v3, v3
	v_mov_b32_e32 v155, v0
	v_mov_b32_e32 v157, v0
	s_waitcnt lgkmcnt(0)
	v_readfirstlane_b32 s3, v2
	s_add_u32 s13, s3, s38
	v_readfirstlane_b32 s0, v3
	s_addc_u32 s15, s0, 0
	s_lshl_b32 s4, s14, 8
	s_ashr_i32 s5, s4, 31
	s_lshl_b64 s[20:21], s[4:5], 2
	s_add_u32 s5, s13, s20
	s_addc_u32 s13, s15, s21
	s_add_u32 s20, s5, s6
	s_addc_u32 s21, s13, s7
	s_add_u32 s3, s3, s40
	s_addc_u32 s0, s0, 0
	s_add_u32 s3, s3, s41
	s_addc_u32 s0, s0, 0
	s_addk_i32 s4, 0xe000
	s_lshr_b32 s4, s4, 12
	s_mulk_i32 s4, 0x1600
	s_addk_i32 s4, 0x1600
	s_cmp_gt_i32 s14, 31
	s_cselect_b32 s46, s4, 0
	s_lshl_b64 s[4:5], s[46:47], 2
	s_add_u32 s3, s3, s4
	s_addc_u32 s0, s0, s5
	s_lshl_b32 s4, s12, 8
	s_ashr_i32 s5, s4, 31
	s_lshl_b64 s[4:5], s[4:5], 2
	s_add_u32 s3, s3, s4
	s_addc_u32 s0, s0, s5
	s_add_u32 s4, s3, s72
	s_addc_u32 s5, s0, 0
	v_lshl_add_u64 v[2:3], s[4:5], 0, v[154:155]
	v_lshl_add_u64 v[2:3], v[2:3], 0, v[156:157]
	v_mov_b32_e32 v159, v0
	v_mov_b32_e32 v161, v0
	v_lshl_add_u64 v[2:3], v[2:3], 0, v[158:159]
	s_mov_b64 s[4:5], 0x10400000
	v_lshl_add_u64 v[4:5], s[20:21], 0, v[160:161]
	v_mov_b32_e32 v163, v0
	v_lshl_add_u64 v[2:3], v[2:3], 0, s[4:5]
	v_lshl_add_u64 v[4:5], v[4:5], 0, v[162:163]
	s_mov_b64 s[4:5], 0x310000
	s_mov_b32 m0, s44
	v_lshl_add_u64 v[6:7], v[4:5], 0, s[4:5]
	s_mov_b64 s[4:5], 0x310200
	global_load_lds_dword v[6:7], off
	v_lshl_add_u64 v[4:5], v[4:5], 0, s[4:5]
	s_mov_b32 m0, s45
	s_andn2_b64 vcc, exec, s[8:9]
	global_load_lds_dword v[4:5], off
	s_mov_b32 m0, s60
	s_nop 0
	global_load_lds_dword v[2:3], off
	s_cbranch_vccnz .LBB0_251
	s_barrier
	s_branch .LBB0_251

.LBB0_271:
	s_lshl_b32 s0, s3, 2
	v_mov_b32_e32 v46, s88
	v_mov_b32_e32 v47, s89
	s_or_b32 s0, s0, s14
	ds_read_b32 v46, v46
	ds_read_b32 v47, v47
	s_mulk_i32 s0, 0x300
	s_add_i32 s0, s0, 0
	s_add_i32 s0, s0, 0x20400
	v_lshl_add_u32 v1, v1, 2, s0
	s_waitcnt lgkmcnt(0)
	v_readfirstlane_b32 s1, v47
	v_readfirstlane_b32 s3, v46
	ds_read2_b32 v[46:47], v1 offset1:16
	v_lshrrev_b32_e32 v83, 4, v66
	v_mov_b32_e32 v92, s3
	v_mov_b32_e32 v93, s1
	s_waitcnt lgkmcnt(0)
	v_fmamk_f32 v46, v46, 0x3a800000, v229
	v_cmp_gt_f32_e32 vcc, s92, v46
	v_mul_f32_e32 v48, 0x4b800000, v46
	s_nop 0
	v_cndmask_b32_e32 v46, v46, v48, vcc
	v_rsq_f32_e32 v46, v46
	s_nop 0
	v_mul_f32_e32 v48, 0x45800000, v46
	v_cndmask_b32_e32 v90, v46, v48, vcc
	v_fmamk_f32 v46, v47, 0x3a800000, v229
	v_cmp_gt_f32_e32 vcc, s92, v46
	v_mul_f32_e32 v47, 0x4b800000, v46
	s_nop 0
	v_cndmask_b32_e32 v46, v46, v47, vcc
	v_rsq_f32_e32 v46, v46
	s_nop 0
	v_mul_f32_e32 v47, 0x45800000, v46
	v_cndmask_b32_e32 v88, v46, v47, vcc
	ds_read2_b32 v[46:47], v1 offset0:32 offset1:48
	s_waitcnt lgkmcnt(0)
	v_fmamk_f32 v1, v46, 0x3a800000, v229
	v_cmp_gt_f32_e32 vcc, s92, v1
	v_mul_f32_e32 v46, 0x4b800000, v1
	s_nop 0
	v_cndmask_b32_e32 v1, v1, v46, vcc
	v_rsq_f32_e32 v1, v1
	s_nop 0
	v_mul_f32_e32 v46, 0x45800000, v1
	v_cndmask_b32_e32 v86, v1, v46, vcc
	v_fmamk_f32 v1, v47, 0x3a800000, v229
	v_cmp_gt_f32_e32 vcc, s92, v1
	v_mul_f32_e32 v46, 0x4b800000, v1
	s_nop 0
	v_cndmask_b32_e32 v1, v1, v46, vcc
	v_rsq_f32_e32 v1, v1
	s_nop 0
	v_mul_f32_e32 v46, 0x45800000, v1
	v_cndmask_b32_e32 v84, v1, v46, vcc
	v_lshl_add_u32 v1, v83, 6, s0
	ds_read_b128 v[66:69], v1 offset:512
	ds_read_b128 v[50:53], v1 offset:528
	ds_read_b128 v[62:65], v1 offset:544
	ds_read_b128 v[46:49], v1 offset:560
	v_readlane_b32 s0, v254, 10
	s_waitcnt lgkmcnt(0)
	v_pk_fma_f32 v[78:79], v[78:79], v[90:91], v[66:67] op_sel_hi:[1,0,1]
	v_pk_fma_f32 v[70:71], v[70:71], v[90:91], v[50:51] op_sel_hi:[1,0,1]
	v_mul_f32_e32 v85, 0xbfb8aa3b, v78
	v_exp_f32_e32 v85, v85
	v_lshl_or_b32 v1, v83, 3, s0
	v_or_b32_e32 v94, s21, v1
	v_readlane_b32 s0, v254, 9
	v_ashrrev_i32_e32 v95, 31, v94
	v_add_f32_e32 v85, 1.0, v85
	v_add_u32_e32 v1, s0, v82
	v_lshl_add_u64 v[82:83], v[94:95], 1, v[92:93]
	v_rcp_f32_e32 v92, v85
	v_mul_f32_e32 v85, 0xbfb8aa3b, v79
	v_exp_f32_e32 v85, v85
	v_pk_fma_f32 v[74:75], v[74:75], v[90:91], v[62:63] op_sel_hi:[1,0,1]
	v_pk_fma_f32 v[76:77], v[76:77], v[90:91], v[64:65] op_sel_hi:[1,0,1]
	v_pk_fma_f32 v[58:59], v[58:59], v[90:91], v[46:47] op_sel_hi:[1,0,1]
	v_add_f32_e32 v85, 1.0, v85
	v_rcp_f32_e32 v93, v85
	v_pk_fma_f32 v[60:61], v[60:61], v[90:91], v[48:49] op_sel_hi:[1,0,1]
	v_lshl_add_u64 v[82:83], v[82:83], 0, s[78:79]
	v_pk_fma_f32 v[54:55], v[54:55], v[88:89], v[66:67] op_sel_hi:[1,0,1]
	v_pk_mul_f32 v[78:79], v[78:79], v[92:93]
	v_pk_fma_f32 v[42:43], v[42:43], v[88:89], v[62:63] op_sel_hi:[1,0,1]
	v_pk_mul_f32 v[74:75], v[74:75], v[78:79]
	v_pk_fma_f32 v[78:79], v[80:81], v[90:91], v[68:69] op_sel_hi:[1,0,1]
	v_pk_fma_f32 v[44:45], v[44:45], v[88:89], v[64:65] op_sel_hi:[1,0,1]
	v_mul_f32_e32 v80, 0xbfb8aa3b, v78
	v_mul_f32_e32 v81, 0xbfb8aa3b, v79
	v_exp_f32_e32 v80, v80
	v_exp_f32_e32 v81, v81
	v_pk_fma_f32 v[38:39], v[38:39], v[88:89], v[50:51] op_sel_hi:[1,0,1]
	v_pk_fma_f32 v[34:35], v[34:35], v[88:89], v[46:47] op_sel_hi:[1,0,1]
	v_add_f32_e32 v80, 1.0, v80
	v_add_f32_e32 v81, 1.0, v81
	v_rcp_f32_e32 v80, v80
	v_rcp_f32_e32 v81, v81
	v_pk_fma_f32 v[36:37], v[36:37], v[88:89], v[48:49] op_sel_hi:[1,0,1]
	v_pk_fma_f32 v[30:31], v[30:31], v[86:87], v[66:67] op_sel_hi:[1,0,1]
	v_pk_fma_f32 v[26:27], v[26:27], v[86:87], v[62:63] op_sel_hi:[1,0,1]
	v_pk_mul_f32 v[78:79], v[78:79], v[80:81]
	v_pk_fma_f32 v[28:29], v[28:29], v[86:87], v[64:65] op_sel_hi:[1,0,1]
	v_pk_mul_f32 v[76:77], v[76:77], v[78:79]
	v_mul_f32_e32 v78, 0xbfb8aa3b, v70
	v_mul_f32_e32 v79, 0xbfb8aa3b, v71
	v_exp_f32_e32 v78, v78
	v_exp_f32_e32 v79, v79
	v_pk_fma_f32 v[22:23], v[22:23], v[86:87], v[50:51] op_sel_hi:[1,0,1]
	v_pk_fma_f32 v[18:19], v[18:19], v[86:87], v[46:47] op_sel_hi:[1,0,1]
	v_add_f32_e32 v78, 1.0, v78
	v_add_f32_e32 v79, 1.0, v79
	v_rcp_f32_e32 v78, v78
	v_rcp_f32_e32 v79, v79
	v_pk_fma_f32 v[20:21], v[20:21], v[86:87], v[48:49] op_sel_hi:[1,0,1]
	v_pk_fma_f32 v[14:15], v[14:15], v[84:85], v[66:67] op_sel_hi:[1,0,1]
	v_pk_fma_f32 v[10:11], v[10:11], v[84:85], v[62:63] op_sel_hi:[1,0,1]
	v_pk_mul_f32 v[70:71], v[70:71], v[78:79]
	v_mad_i64_i32 v[78:79], s[4:5], v1, s71, v[82:83]
	v_pk_mul_f32 v[70:71], v[58:59], v[70:71]
	v_pk_fma_f32 v[58:59], v[72:73], v[90:91], v[52:53] op_sel_hi:[1,0,1]
	v_pk_fma_f32 v[12:13], v[12:13], v[84:85], v[64:65] op_sel_hi:[1,0,1]
	v_mul_f32_e32 v72, 0xbfb8aa3b, v58
	v_mul_f32_e32 v73, 0xbfb8aa3b, v59
	v_exp_f32_e32 v72, v72
	v_exp_f32_e32 v73, v73
	v_pk_fma_f32 v[6:7], v[6:7], v[84:85], v[50:51] op_sel_hi:[1,0,1]
	v_pk_fma_f32 v[2:3], v[2:3], v[84:85], v[46:47] op_sel_hi:[1,0,1]
	v_add_f32_e32 v72, 1.0, v72
	v_add_f32_e32 v73, 1.0, v73
	v_rcp_f32_e32 v72, v72
	v_rcp_f32_e32 v73, v73
	v_pk_fma_f32 v[4:5], v[4:5], v[84:85], v[48:49] op_sel_hi:[1,0,1]
	v_pk_mul_f32 v[58:59], v[58:59], v[72:73]
	s_nop 0
	v_pk_mul_f32 v[72:73], v[60:61], v[58:59]
	v_cvt_pk_bf16_f32 v58, v74, v75
	v_cvt_pk_bf16_f32 v59, v76, v77
	v_cvt_pk_bf16_f32 v60, v70, v71
	v_cvt_pk_bf16_f32 v61, v72, v73
	global_store_dwordx4 v[78:79], v[58:61], off sc1
	s_nop 1
	v_mul_f32_e32 v58, 0xbfb8aa3b, v54
	v_mul_f32_e32 v59, 0xbfb8aa3b, v55
	v_exp_f32_e32 v58, v58
	v_exp_f32_e32 v59, v59
	v_or_b32_e32 v60, 16, v1
	v_add_f32_e32 v58, 1.0, v58
	v_add_f32_e32 v59, 1.0, v59
	v_rcp_f32_e32 v58, v58
	v_rcp_f32_e32 v59, v59
	s_nop 0
	v_pk_mul_f32 v[54:55], v[54:55], v[58:59]
	s_nop 0
	v_pk_mul_f32 v[42:43], v[42:43], v[54:55]
	v_pk_fma_f32 v[54:55], v[56:57], v[88:89], v[68:69] op_sel_hi:[1,0,1]
	s_nop 0
	v_mul_f32_e32 v56, 0xbfb8aa3b, v54
	v_mul_f32_e32 v57, 0xbfb8aa3b, v55
	v_exp_f32_e32 v56, v56
	v_exp_f32_e32 v57, v57
	v_add_f32_e32 v56, 1.0, v56
	v_add_f32_e32 v57, 1.0, v57
	v_rcp_f32_e32 v56, v56
	v_rcp_f32_e32 v57, v57
	s_nop 0
	v_pk_mul_f32 v[54:55], v[54:55], v[56:57]
	s_nop 0
	v_pk_mul_f32 v[44:45], v[44:45], v[54:55]
	v_mul_f32_e32 v54, 0xbfb8aa3b, v38
	v_mul_f32_e32 v55, 0xbfb8aa3b, v39
	v_exp_f32_e32 v54, v54
	v_exp_f32_e32 v55, v55
	v_add_f32_e32 v54, 1.0, v54
	v_add_f32_e32 v55, 1.0, v55
	v_rcp_f32_e32 v54, v54
	v_rcp_f32_e32 v55, v55
	s_nop 0
	v_pk_mul_f32 v[38:39], v[38:39], v[54:55]
	s_nop 0
	v_pk_mul_f32 v[38:39], v[34:35], v[38:39]
	v_pk_fma_f32 v[34:35], v[40:41], v[88:89], v[52:53] op_sel_hi:[1,0,1]
	v_mad_i64_i32 v[54:55], s[4:5], v60, s71, v[82:83]
	v_mul_f32_e32 v40, 0xbfb8aa3b, v34
	v_mul_f32_e32 v41, 0xbfb8aa3b, v35
	v_exp_f32_e32 v40, v40
	v_exp_f32_e32 v41, v41
	v_add_f32_e32 v40, 1.0, v40
	v_add_f32_e32 v41, 1.0, v41
	v_rcp_f32_e32 v40, v40
	v_rcp_f32_e32 v41, v41
	s_nop 0
	v_pk_mul_f32 v[34:35], v[34:35], v[40:41]
	s_nop 0
	v_pk_mul_f32 v[40:41], v[36:37], v[34:35]
	v_cvt_pk_bf16_f32 v34, v42, v43
	v_cvt_pk_bf16_f32 v35, v44, v45
	v_cvt_pk_bf16_f32 v36, v38, v39
	v_cvt_pk_bf16_f32 v37, v40, v41
	global_store_dwordx4 v[54:55], v[34:37], off sc1
	s_nop 1
	v_mul_f32_e32 v34, 0xbfb8aa3b, v30
	v_mul_f32_e32 v35, 0xbfb8aa3b, v31
	v_exp_f32_e32 v34, v34
	v_exp_f32_e32 v35, v35
	v_or_b32_e32 v36, 32, v1
	v_or_b32_e32 v1, 48, v1
	v_add_f32_e32 v34, 1.0, v34
	v_add_f32_e32 v35, 1.0, v35
	v_rcp_f32_e32 v34, v34
	v_rcp_f32_e32 v35, v35
	s_nop 0
	v_pk_mul_f32 v[30:31], v[30:31], v[34:35]
	s_nop 0
	v_pk_mul_f32 v[26:27], v[26:27], v[30:31]
	v_pk_fma_f32 v[30:31], v[32:33], v[86:87], v[68:69] op_sel_hi:[1,0,1]
	s_nop 0
	v_mul_f32_e32 v32, 0xbfb8aa3b, v30
	v_mul_f32_e32 v33, 0xbfb8aa3b, v31
	v_exp_f32_e32 v32, v32
	v_exp_f32_e32 v33, v33
	v_add_f32_e32 v32, 1.0, v32
	v_add_f32_e32 v33, 1.0, v33
	v_rcp_f32_e32 v32, v32
	v_rcp_f32_e32 v33, v33
	s_nop 0
	v_pk_mul_f32 v[30:31], v[30:31], v[32:33]
	s_nop 0
	v_pk_mul_f32 v[28:29], v[28:29], v[30:31]
	v_mul_f32_e32 v30, 0xbfb8aa3b, v22
	v_mul_f32_e32 v31, 0xbfb8aa3b, v23
	v_exp_f32_e32 v30, v30
	v_exp_f32_e32 v31, v31
	v_add_f32_e32 v30, 1.0, v30
	v_add_f32_e32 v31, 1.0, v31
	v_rcp_f32_e32 v30, v30
	v_rcp_f32_e32 v31, v31
	s_nop 0
	v_pk_mul_f32 v[22:23], v[22:23], v[30:31]
	s_nop 0
	v_pk_mul_f32 v[22:23], v[18:19], v[22:23]
	v_pk_fma_f32 v[18:19], v[24:25], v[86:87], v[52:53] op_sel_hi:[1,0,1]
	v_mad_i64_i32 v[30:31], s[4:5], v36, s71, v[82:83]
	v_mul_f32_e32 v24, 0xbfb8aa3b, v18
	v_mul_f32_e32 v25, 0xbfb8aa3b, v19
	v_exp_f32_e32 v24, v24
	v_exp_f32_e32 v25, v25
	v_add_f32_e32 v24, 1.0, v24
	v_add_f32_e32 v25, 1.0, v25
	v_rcp_f32_e32 v24, v24
	v_rcp_f32_e32 v25, v25
	s_nop 0
	v_pk_mul_f32 v[18:19], v[18:19], v[24:25]
	s_nop 0
	v_pk_mul_f32 v[24:25], v[20:21], v[18:19]
	v_cvt_pk_bf16_f32 v18, v26, v27
	v_cvt_pk_bf16_f32 v19, v28, v29
	v_cvt_pk_bf16_f32 v20, v22, v23
	v_cvt_pk_bf16_f32 v21, v24, v25
	global_store_dwordx4 v[30:31], v[18:21], off sc1
	s_nop 1
	v_mul_f32_e32 v18, 0xbfb8aa3b, v14
	v_mul_f32_e32 v19, 0xbfb8aa3b, v15
	v_exp_f32_e32 v18, v18
	v_exp_f32_e32 v19, v19
	v_add_f32_e32 v18, 1.0, v18
	v_add_f32_e32 v19, 1.0, v19
	v_rcp_f32_e32 v18, v18
	v_rcp_f32_e32 v19, v19
	s_nop 0
	v_pk_mul_f32 v[14:15], v[14:15], v[18:19]
	s_nop 0
	v_pk_mul_f32 v[10:11], v[10:11], v[14:15]
	v_pk_fma_f32 v[14:15], v[16:17], v[84:85], v[68:69] op_sel_hi:[1,0,1]
	s_nop 0
	v_mul_f32_e32 v16, 0xbfb8aa3b, v14
	v_mul_f32_e32 v17, 0xbfb8aa3b, v15
	v_exp_f32_e32 v16, v16
	v_exp_f32_e32 v17, v17
	v_add_f32_e32 v16, 1.0, v16
	v_add_f32_e32 v17, 1.0, v17
	v_rcp_f32_e32 v16, v16
	v_rcp_f32_e32 v17, v17
	s_nop 0
	v_pk_mul_f32 v[14:15], v[14:15], v[16:17]
	s_nop 0
	v_pk_mul_f32 v[12:13], v[12:13], v[14:15]
	v_mul_f32_e32 v14, 0xbfb8aa3b, v6
	v_mul_f32_e32 v15, 0xbfb8aa3b, v7
	v_exp_f32_e32 v14, v14
	v_exp_f32_e32 v15, v15
	v_add_f32_e32 v14, 1.0, v14
	v_add_f32_e32 v15, 1.0, v15
	v_rcp_f32_e32 v14, v14
	v_rcp_f32_e32 v15, v15
	s_nop 0
	v_pk_mul_f32 v[6:7], v[6:7], v[14:15]
	s_nop 0
	v_pk_mul_f32 v[6:7], v[2:3], v[6:7]
	v_pk_fma_f32 v[2:3], v[8:9], v[84:85], v[52:53] op_sel_hi:[1,0,1]
	v_mad_i64_i32 v[14:15], s[4:5], v1, s71, v[82:83]
	v_mul_f32_e32 v8, 0xbfb8aa3b, v2
	v_mul_f32_e32 v9, 0xbfb8aa3b, v3
	v_exp_f32_e32 v8, v8
	v_exp_f32_e32 v9, v9
	v_add_f32_e32 v8, 1.0, v8
	v_add_f32_e32 v9, 1.0, v9
	v_rcp_f32_e32 v8, v8
	v_rcp_f32_e32 v9, v9
	s_nop 0
	v_pk_mul_f32 v[2:3], v[2:3], v[8:9]
	s_nop 0
	v_pk_mul_f32 v[8:9], v[4:5], v[2:3]
	v_cvt_pk_bf16_f32 v2, v10, v11
	v_cvt_pk_bf16_f32 v3, v12, v13
	v_cvt_pk_bf16_f32 v4, v6, v7
	v_cvt_pk_bf16_f32 v5, v8, v9
	global_store_dwordx4 v[14:15], v[2:5], off sc1
	s_waitcnt vmcnt(0)
	s_barrier
